# LN phase row loop: counted vmcnt(8) instead of full drain (next-row loads older than this rows 8 stores), on top of S5-out software pipelining and compact relu^2 epilogue
# speedup vs baseline: 1.0031x; 1.0031x over previous
; #define GAS __attribute__((address_space(1)))
; __device__ __forceinline__ void phase_ln(const bool HAS_H, bf16_t* zx, float* dout, const float* g, const float* b, const float* scale, const float* shift, bf16_t* H, int lane, int wave) {
;     ...
;     for (int row = gw; row < SEQ; row += NGW) { bf16_t* zr = zx + (size_t)row * DM + 8 * lane;
;         f32x4 v[8]; float s = 0.f;
;         u32x4 wc_[4];
; #pragma unroll
;         for (int j = 0; j < 4; ++j) wc_[j] = wn[j];
;         if (row + NGW < SEQ) {
; #pragma unroll
;             for (int j = 0; j < 4; ++j) wn[j] = *(const GAS u32x4*)(zr + (size_t)NGW * DM + 512 * j); }
.LBB0_224:
	v_readlane_b32 s0, v252, 8
	v_readlane_b32 s1, v252, 9
	s_waitcnt vmcnt(8)
	v_mov_b64_e32 v[118:119], v[102:103]
	v_mov_b64_e32 v[122:123], v[106:107]
	v_mov_b64_e32 v[126:127], v[110:111]
	v_mov_b64_e32 v[130:131], v[114:115]
	v_lshl_add_u64 v[168:169], v[168:169], 0, s[0:1]
	s_andn2_b64 vcc, exec, s[4:5]
	v_mov_b64_e32 v[170:171], v[172:173]
	v_mov_b64_e32 v[116:117], v[100:101]
	v_mov_b64_e32 v[120:121], v[104:105]
	v_mov_b64_e32 v[124:125], v[108:109]
	v_mov_b64_e32 v[128:129], v[112:113]
	s_cbranch_vccz .LBB0_243
